# attention tile loop: cross-half row max via v_permlane32_swap instead of ds_bpermute + lgkmcnt(0) (on top of V^T b32 staging)
# baseline (speedup 1.0000x reference)
.LBB0_514:
	s_nop 1
	v_max3_f32 v136, v48, v49, v50
	v_max3_f32 v137, v64, v65, v66
	v_max3_f32 v136, v136, v51, v52
	v_max3_f32 v137, v137, v67, v68
	v_max3_f32 v136, v136, v53, v54
	v_max3_f32 v137, v137, v69, v70
	v_max3_f32 v136, v136, v55, v56
	v_max3_f32 v137, v137, v71, v72
	v_max3_f32 v136, v136, v57, v58
	v_max3_f32 v137, v137, v73, v74
	v_max3_f32 v136, v136, v59, v60
	v_max3_f32 v137, v137, v75, v76
	v_max3_f32 v136, v136, v61, v62
	v_max3_f32 v137, v137, v77, v78
	v_max3_f32 v136, v136, v63, v79
	v_max_f32_e32 v136, v136, v137
	v_mov_b32_e32 v137, v136
	s_nop 1
	v_permlane32_swap_b32 v137, v136
	v_max_f32_e32 v136, v136, v137
	v_cmp_lt_f32_e32 vcc, s52, v136
	s_cmp_lg_u64 vcc, 0
	s_cselect_b64 s[38:39], -1, 0
	s_cbranch_vccz .LBB0_516
	v_max_f32_e32 v0, v136, v136
	v_max_f32_e32 v2, 0, v0
	v_exp_f32_e64 v136, -v2
	v_add_f32_e32 v146, v146, v2
	v_xor_b32_e32 v0, 0x80000000, v146
	v_pk_add_f32 v[48:49], v[48:49], v[2:3] op_sel_hi:[1,0] neg_lo:[0,1] neg_hi:[0,1]
	v_pk_add_f32 v[64:65], v[64:65], v[2:3] op_sel_hi:[1,0] neg_lo:[0,1] neg_hi:[0,1]
	v_pk_add_f32 v[50:51], v[50:51], v[2:3] op_sel_hi:[1,0] neg_lo:[0,1] neg_hi:[0,1]
	v_pk_add_f32 v[66:67], v[66:67], v[2:3] op_sel_hi:[1,0] neg_lo:[0,1] neg_hi:[0,1]
	v_pk_add_f32 v[52:53], v[52:53], v[2:3] op_sel_hi:[1,0] neg_lo:[0,1] neg_hi:[0,1]
	v_pk_add_f32 v[68:69], v[68:69], v[2:3] op_sel_hi:[1,0] neg_lo:[0,1] neg_hi:[0,1]
	v_pk_add_f32 v[54:55], v[54:55], v[2:3] op_sel_hi:[1,0] neg_lo:[0,1] neg_hi:[0,1]
	v_pk_add_f32 v[70:71], v[70:71], v[2:3] op_sel_hi:[1,0] neg_lo:[0,1] neg_hi:[0,1]
	v_pk_add_f32 v[56:57], v[56:57], v[2:3] op_sel_hi:[1,0] neg_lo:[0,1] neg_hi:[0,1]
	v_pk_add_f32 v[72:73], v[72:73], v[2:3] op_sel_hi:[1,0] neg_lo:[0,1] neg_hi:[0,1]
	v_pk_add_f32 v[58:59], v[58:59], v[2:3] op_sel_hi:[1,0] neg_lo:[0,1] neg_hi:[0,1]
	v_pk_add_f32 v[74:75], v[74:75], v[2:3] op_sel_hi:[1,0] neg_lo:[0,1] neg_hi:[0,1]
	v_pk_add_f32 v[60:61], v[60:61], v[2:3] op_sel_hi:[1,0] neg_lo:[0,1] neg_hi:[0,1]
	v_pk_add_f32 v[76:77], v[76:77], v[2:3] op_sel_hi:[1,0] neg_lo:[0,1] neg_hi:[0,1]
	v_pk_add_f32 v[62:63], v[62:63], v[2:3] op_sel_hi:[1,0] neg_lo:[0,1] neg_hi:[0,1]
	v_pk_add_f32 v[78:79], v[78:79], v[2:3] op_sel_hi:[1,0] neg_lo:[0,1] neg_hi:[0,1]
	v_mul_f32_e32 v165, v165, v136
	v_mov_b32_e32 v1, v0
	v_mov_b32_e32 v2, v0
	v_mov_b32_e32 v3, v0
	v_mov_b32_e32 v4, v0
	v_mov_b32_e32 v5, v0
	v_mov_b32_e32 v6, v0
	v_mov_b32_e32 v7, v0
	v_mov_b32_e32 v8, v0
	v_mov_b32_e32 v9, v0
	v_mov_b32_e32 v10, v0
	v_mov_b32_e32 v11, v0
	v_mov_b32_e32 v12, v0
	v_mov_b32_e32 v13, v0
	v_mov_b32_e32 v14, v0
	v_mov_b32_e32 v15, v0
	s_branch .LBB0_517
